# row-scale loads issued with the operand loads in the sample-row GEMMs of P1 and P6 as well
# baseline (speedup 1.0000x reference)
.LBB0_320:
	s_ashr_i32 s10, s26, 31
	s_lshr_b32 s10, s10, 29
	s_add_i32 s10, s26, s10
	s_ashr_i32 s13, s10, 3
	s_lshl_b32 s10, s13, 8
	s_sub_i32 s12, 0, s10
	v_mov_b32_e32 v2, 1.0
	s_and_saveexec_b64 s[10:11], s[4:5]
	s_cbranch_execz .LBB0_322
	s_add_i32 s14, s12, s9
	v_add_u32_e32 v0, s14, v23
	v_add_u32_e32 v0, 0x4000, v0
	v_ashrrev_i32_e32 v1, 31, v0
	v_lshl_add_u64 v[120:121], v[0:1], 3, s[54:55]
	global_load_dwordx2 v[120:121], v[120:121], off
.LBB0_322:
	s_or_b64 exec, exec, s[10:11]
	s_lshl_b32 s13, s13, 5
	v_or_b32_e32 v10, s13, v18
	v_ashrrev_i32_e32 v11, 31, v10
	v_lshlrev_b64 v[10:11], 11, v[10:11]
	s_add_i32 s12, s12, s9
	v_lshl_add_u64 v[54:55], v[8:9], 0, v[10:11]
	v_add_u32_e32 v0, s12, v18
	s_waitcnt lgkmcnt(0)
	global_load_dwordx4 v[10:13], v[54:55], off
	v_ashrrev_i32_e32 v1, 31, v0
	v_lshlrev_b64 v[0:1], 11, v[0:1]
	v_lshl_add_u64 v[0:1], v[6:7], 0, v[0:1]
	global_load_dwordx4 v[14:17], v[0:1], off
	v_add_co_u32_e32 v62, vcc, 0x8000, v0
	s_waitcnt vmcnt(0)
	v_mfma_f32_16x16x32_bf16 v[38:41], v[10:13], v[14:17], 0
	v_addc_co_u32_e32 v63, vcc, 0, v1, vcc
	global_load_dwordx4 v[26:29], v[62:63], off
	global_load_dwordx4 v[30:33], v[0:1], off offset:64
	global_load_dwordx4 v[34:37], v[54:55], off offset:64
	s_and_saveexec_b64 s[10:11], s[4:5]
	v_ffbh_u32_e32 v122, v121
	v_min_u32_e32 v122, 32, v122
	v_lshlrev_b64 v[120:121], v122, v[120:121]
	v_min_u32_e32 v120, 1, v120
	v_or_b32_e32 v120, v121, v120
	v_cvt_f32_u32_e32 v120, v120
	v_sub_u32_e32 v121, 32, v122
	v_ldexp_f32 v120, v120, v121
	v_fmamk_f32 v120, v120, 0x30800000, v24
	v_mul_f32_e32 v121, 0x4b800000, v120
	v_cmp_gt_f32_e32 vcc, s20, v120
	s_nop 1
	v_cndmask_b32_e32 v120, v120, v121, vcc
	v_rsq_f32_e32 v120, v120
	s_nop 0
	v_mul_f32_e32 v121, 0x45800000, v120
	v_cndmask_b32_e32 v2, v120, v121, vcc
	s_or_b64 exec, exec, s[10:11]
	v_add_co_u32_e32 v64, vcc, 0x8000, v54
	s_waitcnt vmcnt(2)
	v_mfma_f32_16x16x32_bf16 v[10:13], v[10:13], v[26:29], 0
	v_addc_co_u32_e32 v65, vcc, 0, v55, vcc
	global_load_dwordx4 v[42:45], v[64:65], off
	global_load_dwordx4 v[46:49], v[62:63], off offset:64
	global_load_dwordx4 v[50:53], v[64:65], off offset:64
	s_waitcnt vmcnt(2)
	v_mfma_f32_16x16x32_bf16 v[14:17], v[42:45], v[14:17], 0
	v_mfma_f32_16x16x32_bf16 v[38:41], v[34:37], v[30:33], v[38:41]
	s_waitcnt vmcnt(1)
	v_mfma_f32_16x16x32_bf16 v[10:13], v[34:37], v[46:49], v[10:13]
	global_load_dwordx4 v[34:37], v[54:55], off offset:128
	v_mfma_f32_16x16x32_bf16 v[26:29], v[42:45], v[26:29], 0
	s_waitcnt vmcnt(1)
	v_mfma_f32_16x16x32_bf16 v[14:17], v[50:53], v[30:33], v[14:17]
	global_load_dwordx4 v[30:33], v[0:1], off offset:128
	v_mfma_f32_16x16x32_bf16 v[26:29], v[50:53], v[46:49], v[26:29]
	global_load_dwordx4 v[42:45], v[62:63], off offset:128
	global_load_dwordx4 v[46:49], v[0:1], off offset:192
	global_load_dwordx4 v[50:53], v[54:55], off offset:192
	s_nop 0
	global_load_dwordx4 v[54:57], v[64:65], off offset:128
	global_load_dwordx4 v[58:61], v[62:63], off offset:192
	s_waitcnt vmcnt(5)
	v_mfma_f32_16x16x32_bf16 v[38:41], v[34:37], v[30:33], v[38:41]
	s_waitcnt vmcnt(4)
	v_mfma_f32_16x16x32_bf16 v[10:13], v[34:37], v[42:45], v[10:13]
	global_load_dwordx4 v[34:37], v[64:65], off offset:192
	s_waitcnt vmcnt(2)
	v_mfma_f32_16x16x32_bf16 v[14:17], v[54:57], v[30:33], v[14:17]
	v_mfma_f32_16x16x32_bf16 v[26:29], v[54:57], v[42:45], v[26:29]
	v_mfma_f32_16x16x32_bf16 v[30:33], v[50:53], v[46:49], v[38:41]
	s_waitcnt vmcnt(1)
	v_mfma_f32_16x16x32_bf16 v[10:13], v[50:53], v[58:61], v[10:13]
	s_waitcnt vmcnt(0)
	v_mfma_f32_16x16x32_bf16 v[14:17], v[34:37], v[46:49], v[14:17]
	v_mfma_f32_16x16x32_bf16 v[26:29], v[34:37], v[58:61], v[26:29]
	s_nop 2
	ds_write_b128 v25, v[30:33]
	s_nop 0
	ds_write_b128 v25, v[10:13] offset:2048
	s_nop 0
	ds_write_b128 v25, v[14:17] offset:1024
	ds_write_b128 v25, v[26:29] offset:3072
	s_waitcnt lgkmcnt(0)
	s_barrier
	s_and_saveexec_b64 s[10:11], s[4:5]
	s_cbranch_execz .LBB0_319
	ds_read_b128 v[14:17], v20
	ds_read_b128 v[26:29], v21 offset:4096
	ds_read_b128 v[30:33], v21 offset:8192
	ds_read_b128 v[34:37], v21 offset:12288
	v_add_u32_e32 v0, s12, v23
	v_add_u32_e32 v12, 0x4000, v0
	s_waitcnt lgkmcnt(2)
	v_pk_add_f32 v[0:1], v[16:17], v[28:29]
	v_pk_add_f32 v[26:27], v[14:15], v[26:27]
	ds_read_b128 v[14:17], v21 offset:16384
	s_waitcnt lgkmcnt(2)
	v_pk_add_f32 v[26:27], v[26:27], v[30:31]
	v_pk_add_f32 v[0:1], v[0:1], v[32:33]
	s_waitcnt lgkmcnt(1)
	v_pk_add_f32 v[34:35], v[26:27], v[34:35]
	ds_read_b128 v[26:29], v21 offset:20480
	v_pk_add_f32 v[0:1], v[0:1], v[36:37]
	ds_read_b128 v[30:33], v21 offset:24576
	s_waitcnt lgkmcnt(2)
	v_pk_add_f32 v[0:1], v[0:1], v[16:17]
	v_pk_add_f32 v[34:35], v[34:35], v[14:15]
	ds_read_b128 v[14:17], v21 offset:28672
	s_waitcnt lgkmcnt(2)
	v_pk_add_f32 v[0:1], v[0:1], v[28:29]
	v_pk_add_f32 v[26:27], v[34:35], v[26:27]
	s_waitcnt lgkmcnt(1)
	v_pk_add_f32 v[0:1], v[0:1], v[32:33]
	v_pk_add_f32 v[26:27], v[26:27], v[30:31]
	s_waitcnt lgkmcnt(0)
	v_pk_add_f32 v[16:17], v[0:1], v[16:17]
	v_pk_add_f32 v[0:1], v[26:27], v[14:15]
	v_add_u32_e32 v10, s13, v22
	v_ashrrev_i32_e32 v13, 31, v12
	v_pk_mul_f32 v[0:1], v[2:3], v[0:1] op_sel_hi:[0,1]
	v_pk_mul_f32 v[2:3], v[2:3], v[16:17] op_sel_hi:[0,1]
	v_lshlrev_b64 v[38:39], 11, v[12:13]
	v_pk_mul_f32 v[16:17], v[0:1], s[8:9] op_sel_hi:[1,0]
	v_pk_mul_f32 v[26:27], v[2:3], s[8:9] op_sel_hi:[1,0]
	v_cmp_gt_i32_e32 vcc, s21, v10
	v_ashrrev_i32_e32 v11, 31, v10
	v_lshl_add_u64 v[14:15], s[68:69], 0, v[38:39]
	v_cndmask_b32_e32 v4, v27, v3, vcc
	v_cndmask_b32_e32 v13, v26, v2, vcc
	v_cndmask_b32_e32 v17, v17, v1, vcc
	v_cndmask_b32_e32 v16, v16, v0, vcc
	v_lshl_add_u64 v[14:15], v[10:11], 1, v[14:15]
	v_cvt_pk_bf16_f32 v16, v16, v17
	v_cvt_pk_bf16_f32 v17, v13, v4
	global_store_dwordx2 v[14:15], v[16:17], off
	s_and_b64 exec, exec, vcc
	s_cbranch_execz .LBB0_319
	v_add_u32_e32 v4, s12, v19
	v_cmp_lt_i32_e32 vcc, s22, v12
	s_mov_b64 s[12:13], 0
	s_and_saveexec_b64 s[14:15], vcc
	s_xor_b64 s[14:15], exec, s[14:15]
	s_cbranch_execz .LBB0_327
	v_lshrrev_b32_e32 v4, 5, v4
	v_and_b32_e32 v12, 31, v12
	v_mul_lo_u32 v4, v4, 15
	v_add3_u32 v4, v4, v12, s23
	v_cmp_lt_u32_e32 vcc, 16, v12
	s_and_b64 s[12:13], vcc, exec
	v_mov_b64_e32 v[14:15], v[4:5]
	s_or_saveexec_b64 s[14:15], s[14:15]
	v_mov_b64_e32 v[16:17], 0x850f000
	s_xor_b64 exec, exec, s[14:15]
	s_cbranch_execnz .LBB0_328

.LBB0_333:
	s_ashr_i32 s10, s18, 31
	s_lshr_b32 s10, s10, 29
	s_add_i32 s10, s18, s10
	s_ashr_i32 s29, s10, 3
	s_lshl_b32 s10, s29, 9
	s_sub_i32 s28, 0, s10
	v_add3_u32 v8, v12, v27, s28
	v_mov_b32_e32 v6, 1.0
	v_ashrrev_i32_e32 v9, 31, v8
	v_mov_b32_e32 v10, 1.0
	s_and_saveexec_b64 s[10:11], s[4:5]
	s_cbranch_execz .LBB0_335
	v_lshl_add_u64 v[148:149], v[8:9], 3, s[8:9]
	global_load_dwordx2 v[148:149], v[148:149], off
.LBB0_335:
	s_or_b64 exec, exec, s[10:11]
	s_and_saveexec_b64 s[10:11], s[6:7]
	s_cbranch_execz .LBB0_337
	v_add3_u32 v150, v13, v27, s28
	v_ashrrev_i32_e32 v151, 31, v150
	v_lshl_add_u64 v[150:151], v[150:151], 3, s[8:9]
	global_load_dwordx2 v[150:151], v[150:151], off
.LBB0_337:
	s_or_b64 exec, exec, s[10:11]
	v_add_u32_e32 v34, s28, v27
	v_ashrrev_i32_e32 v35, 31, v34
	v_lshlrev_b64 v[34:35], 11, v[34:35]
	v_lshl_add_u64 v[132:133], v[2:3], 0, v[34:35]
	v_add_co_u32_e32 v134, vcc, 0x8000, v132
	s_lshl_b32 s29, s29, 6
	s_nop 0
	v_addc_co_u32_e32 v135, vcc, 0, v133, vcc
	v_or_b32_e32 v30, s29, v7
	v_add_co_u32_e32 v138, vcc, s24, v132
	v_ashrrev_i32_e32 v31, 31, v30
	s_nop 0
	v_addc_co_u32_e32 v139, vcc, 0, v133, vcc
	v_lshlrev_b64 v[30:31], 11, v[30:31]
	v_add_co_u32_e32 v146, vcc, s25, v132
	v_lshl_add_u64 v[130:131], v[4:5], 0, v[30:31]
	s_nop 0
	v_addc_co_u32_e32 v147, vcc, 0, v133, vcc
	v_add_co_u32_e32 v136, vcc, 0x8000, v130
	global_load_dwordx4 v[30:33], v[130:131], off
	global_load_dwordx4 v[34:37], v[132:133], off
	v_addc_co_u32_e32 v137, vcc, 0, v131, vcc
	v_add_co_u32_e32 v140, vcc, s24, v130
	global_load_dwordx4 v[38:41], v[132:133], off offset:64
	s_nop 0
	v_addc_co_u32_e32 v141, vcc, 0, v131, vcc
	v_add_co_u32_e32 v142, vcc, s25, v130
	global_load_dwordx4 v[42:45], v[130:131], off offset:64
	global_load_dwordx4 v[46:49], v[134:135], off
	global_load_dwordx4 v[50:53], v[138:139], off
	v_addc_co_u32_e32 v143, vcc, 0, v131, vcc
	global_load_dwordx4 v[58:61], v[146:147], off
	global_load_dwordx4 v[62:65], v[134:135], off offset:64
	global_load_dwordx4 v[70:73], v[138:139], off offset:64
	global_load_dwordx4 v[78:81], v[146:147], off offset:64
	global_load_dwordx4 v[82:85], v[136:137], off
	global_load_dwordx4 v[86:89], v[136:137], off offset:64
	global_load_dwordx4 v[102:105], v[140:141], off
	global_load_dwordx4 v[106:109], v[140:141], off offset:64
	global_load_dwordx4 v[122:125], v[142:143], off
	global_load_dwordx4 v[126:129], v[142:143], off offset:64
	s_waitcnt vmcnt(0)
	s_and_saveexec_b64 s[10:11], s[4:5]
	v_ffbh_u32_e32 v152, v149
	v_min_u32_e32 v152, 32, v152
	v_lshlrev_b64 v[148:149], v152, v[148:149]
	v_min_u32_e32 v148, 1, v148
	v_or_b32_e32 v148, v149, v148
	v_cvt_f32_u32_e32 v148, v148
	v_sub_u32_e32 v149, 32, v152
	v_ldexp_f32 v148, v148, v149
	v_fmamk_f32 v148, v148, 0x30800000, v28
	v_mul_f32_e32 v149, 0x4b800000, v148
	v_cmp_gt_f32_e32 vcc, s27, v148
	s_nop 1
	v_cndmask_b32_e32 v148, v148, v149, vcc
	v_rsq_f32_e32 v148, v148
	s_nop 0
	v_mul_f32_e32 v149, 0x45800000, v148
	v_cndmask_b32_e32 v10, v148, v149, vcc
	s_or_b64 exec, exec, s[10:11]
	s_and_saveexec_b64 s[10:11], s[6:7]
	v_ffbh_u32_e32 v152, v151
	v_min_u32_e32 v152, 32, v152
	v_lshlrev_b64 v[150:151], v152, v[150:151]
	v_min_u32_e32 v150, 1, v150
	v_or_b32_e32 v150, v151, v150
	v_cvt_f32_u32_e32 v150, v150
	v_sub_u32_e32 v151, 32, v152
	v_ldexp_f32 v150, v150, v151
	v_fmamk_f32 v150, v150, 0x30800000, v28
	v_mul_f32_e32 v151, 0x4b800000, v150
	v_cmp_gt_f32_e32 vcc, s27, v150
	s_nop 1
	v_cndmask_b32_e32 v150, v150, v151, vcc
	v_rsq_f32_e32 v150, v150
	s_nop 0
	v_mul_f32_e32 v151, 0x45800000, v150
	v_cndmask_b32_e32 v6, v150, v151, vcc
	s_or_b64 exec, exec, s[10:11]
	v_mfma_f32_16x16x32_bf16 v[54:57], v[30:33], v[34:37], 0
	v_mfma_f32_16x16x32_bf16 v[66:69], v[30:33], v[46:49], 0
	v_mfma_f32_16x16x32_bf16 v[74:77], v[30:33], v[50:53], 0
	v_mfma_f32_16x16x32_bf16 v[30:33], v[30:33], v[58:61], 0
	v_mfma_f32_16x16x32_bf16 v[90:93], v[82:85], v[34:37], 0
	v_mfma_f32_16x16x32_bf16 v[94:97], v[82:85], v[46:49], 0
	v_mfma_f32_16x16x32_bf16 v[98:101], v[82:85], v[50:53], 0
	v_mfma_f32_16x16x32_bf16 v[82:85], v[82:85], v[58:61], 0
	v_mfma_f32_16x16x32_bf16 v[54:57], v[42:45], v[38:41], v[54:57]
	v_mfma_f32_16x16x32_bf16 v[66:69], v[42:45], v[62:65], v[66:69]
	v_mfma_f32_16x16x32_bf16 v[74:77], v[42:45], v[70:73], v[74:77]
	v_mfma_f32_16x16x32_bf16 v[30:33], v[42:45], v[78:81], v[30:33]
	v_mfma_f32_16x16x32_bf16 v[42:45], v[86:89], v[78:81], v[82:85]
	s_nop 2
	global_load_dwordx4 v[82:85], v[130:131], off offset:128
	v_mfma_f32_16x16x32_bf16 v[110:113], v[102:105], v[34:37], 0
	v_mfma_f32_16x16x32_bf16 v[114:117], v[102:105], v[46:49], 0
	v_mfma_f32_16x16x32_bf16 v[118:121], v[102:105], v[50:53], 0
	v_mfma_f32_16x16x32_bf16 v[102:105], v[102:105], v[58:61], 0
	v_mfma_f32_16x16x32_bf16 v[34:37], v[122:125], v[34:37], 0
	v_mfma_f32_16x16x32_bf16 v[46:49], v[122:125], v[46:49], 0
	v_mfma_f32_16x16x32_bf16 v[50:53], v[122:125], v[50:53], 0
	v_mfma_f32_16x16x32_bf16 v[58:61], v[122:125], v[58:61], 0
	v_mfma_f32_16x16x32_bf16 v[90:93], v[86:89], v[38:41], v[90:93]
	v_mfma_f32_16x16x32_bf16 v[94:97], v[86:89], v[62:65], v[94:97]
	v_mfma_f32_16x16x32_bf16 v[110:113], v[106:109], v[38:41], v[110:113]
	v_mfma_f32_16x16x32_bf16 v[114:117], v[106:109], v[62:65], v[114:117]
	v_mfma_f32_16x16x32_bf16 v[34:37], v[126:129], v[38:41], v[34:37]
	v_mfma_f32_16x16x32_bf16 v[38:41], v[126:129], v[62:65], v[46:49]
	v_mfma_f32_16x16x32_bf16 v[46:49], v[86:89], v[70:73], v[98:101]
	v_mfma_f32_16x16x32_bf16 v[62:65], v[106:109], v[70:73], v[118:121]
	v_mfma_f32_16x16x32_bf16 v[50:53], v[126:129], v[70:73], v[50:53]
	v_mfma_f32_16x16x32_bf16 v[70:73], v[106:109], v[78:81], v[102:105]
	v_mfma_f32_16x16x32_bf16 v[58:61], v[126:129], v[78:81], v[58:61]
	global_load_dwordx4 v[78:81], v[132:133], off offset:128
	global_load_dwordx4 v[86:89], v[132:133], off offset:192
	global_load_dwordx4 v[98:101], v[130:131], off offset:192
	global_load_dwordx4 v[102:105], v[136:137], off offset:128
	global_load_dwordx4 v[106:109], v[136:137], off offset:192
	global_load_dwordx4 v[118:121], v[140:141], off offset:128
	global_load_dwordx4 v[122:125], v[140:141], off offset:192
	global_load_dwordx4 v[126:129], v[142:143], off offset:128
	global_load_dwordx4 v[130:133], v[142:143], off offset:192
	s_waitcnt vmcnt(8)
	v_mfma_f32_16x16x32_bf16 v[54:57], v[82:85], v[78:81], v[54:57]
	s_waitcnt vmcnt(5)
	v_mfma_f32_16x16x32_bf16 v[90:93], v[102:105], v[78:81], v[90:93]
	s_waitcnt vmcnt(3)
	v_mfma_f32_16x16x32_bf16 v[110:113], v[118:121], v[78:81], v[110:113]
	s_waitcnt vmcnt(1)
	v_mfma_f32_16x16x32_bf16 v[34:37], v[126:129], v[78:81], v[34:37]
	global_load_dwordx4 v[78:81], v[134:135], off offset:128
	s_nop 0
	global_load_dwordx4 v[134:137], v[134:135], off offset:192
	s_waitcnt vmcnt(1)
	v_mfma_f32_16x16x32_bf16 v[66:69], v[82:85], v[78:81], v[66:69]
	v_mfma_f32_16x16x32_bf16 v[94:97], v[102:105], v[78:81], v[94:97]
	v_mfma_f32_16x16x32_bf16 v[114:117], v[118:121], v[78:81], v[114:117]
	v_mfma_f32_16x16x32_bf16 v[38:41], v[126:129], v[78:81], v[38:41]
	global_load_dwordx4 v[78:81], v[138:139], off offset:128
	s_nop 0
	global_load_dwordx4 v[138:141], v[138:139], off offset:192
	s_nop 0
	global_load_dwordx4 v[142:145], v[146:147], off offset:128
	s_waitcnt vmcnt(2)
	v_mfma_f32_16x16x32_bf16 v[74:77], v[82:85], v[78:81], v[74:77]
	v_mfma_f32_16x16x32_bf16 v[46:49], v[102:105], v[78:81], v[46:49]
	v_mfma_f32_16x16x32_bf16 v[62:65], v[118:121], v[78:81], v[62:65]
	v_mfma_f32_16x16x32_bf16 v[50:53], v[126:129], v[78:81], v[50:53]
	global_load_dwordx4 v[78:81], v[146:147], off offset:192
	s_waitcnt vmcnt(1)
	v_mfma_f32_16x16x32_bf16 v[30:33], v[82:85], v[142:145], v[30:33]
	v_mfma_f32_16x16x32_bf16 v[42:45], v[102:105], v[142:145], v[42:45]
	v_mfma_f32_16x16x32_bf16 v[54:57], v[98:101], v[86:89], v[54:57]
	v_mfma_f32_16x16x32_bf16 v[34:37], v[130:133], v[86:89], v[34:37]
	v_mfma_f32_16x16x32_bf16 v[70:73], v[118:121], v[142:145], v[70:73]
	v_mfma_f32_16x16x32_bf16 v[82:85], v[106:109], v[86:89], v[90:93]
	v_mfma_f32_16x16x32_bf16 v[90:93], v[122:125], v[86:89], v[110:113]
	s_nop 3
	ds_write_b128 v29, v[54:57]
	s_nop 1
	ds_write_b128 v29, v[82:85] offset:1024
	ds_write_b128 v29, v[90:93] offset:2048
	v_mfma_f32_16x16x32_bf16 v[66:69], v[98:101], v[134:137], v[66:69]
	v_mfma_f32_16x16x32_bf16 v[86:89], v[106:109], v[134:137], v[94:97]
	ds_write_b128 v29, v[34:37] offset:3072
	s_nop 5
	ds_write_b128 v29, v[66:69] offset:4096
	ds_write_b128 v29, v[86:89] offset:5120
	v_mfma_f32_16x16x32_bf16 v[94:97], v[122:125], v[134:137], v[114:117]
	v_mfma_f32_16x16x32_bf16 v[38:41], v[130:133], v[134:137], v[38:41]
	v_mfma_f32_16x16x32_bf16 v[58:61], v[126:129], v[142:145], v[58:61]
	v_mfma_f32_16x16x32_bf16 v[74:77], v[98:101], v[138:141], v[74:77]
	s_nop 4
	ds_write_b128 v29, v[94:97] offset:6144
	ds_write_b128 v29, v[38:41] offset:7168
	s_nop 0
	ds_write_b128 v29, v[74:77] offset:8192
	v_mfma_f32_16x16x32_bf16 v[46:49], v[106:109], v[138:141], v[46:49]
	s_waitcnt vmcnt(0)
	v_mfma_f32_16x16x32_bf16 v[30:33], v[98:101], v[78:81], v[30:33]
	v_mfma_f32_16x16x32_bf16 v[62:65], v[122:125], v[138:141], v[62:65]
	v_mfma_f32_16x16x32_bf16 v[34:37], v[106:109], v[78:81], v[42:45]
	v_mfma_f32_16x16x32_bf16 v[50:53], v[130:133], v[138:141], v[50:53]
	s_nop 2
	ds_write_b128 v29, v[46:49] offset:9216
	s_nop 1
	ds_write_b128 v29, v[62:65] offset:10240
	s_nop 0
	ds_write_b128 v29, v[50:53] offset:11264
	v_mfma_f32_16x16x32_bf16 v[38:41], v[122:125], v[78:81], v[70:73]
	ds_write_b128 v29, v[30:33] offset:12288
	ds_write_b128 v29, v[34:37] offset:13312
	s_nop 5
	ds_write_b128 v29, v[38:41] offset:14336
	v_mfma_f32_16x16x32_bf16 v[30:33], v[130:133], v[78:81], v[58:61]
	s_nop 7
	ds_write_b128 v29, v[30:33] offset:15360
	s_waitcnt lgkmcnt(0)
	s_barrier
	s_and_saveexec_b64 s[10:11], s[4:5]
	s_cbranch_execz .LBB0_332
	ds_read_b128 v[30:33], v15 offset:16384
	ds_read_b128 v[34:37], v14
	ds_read_b128 v[38:41], v15 offset:32768
	ds_read_b128 v[42:45], v15 offset:49152
	s_waitcnt lgkmcnt(2)
	v_pk_add_f32 v[32:33], v[36:37], v[32:33]
	v_pk_add_f32 v[34:35], v[34:35], v[30:31]
	s_waitcnt lgkmcnt(1)
	v_pk_add_f32 v[36:37], v[32:33], v[40:41]
	ds_read_b128 v[30:33], v16
	v_pk_add_f32 v[34:35], v[34:35], v[38:39]
	s_waitcnt lgkmcnt(1)
	v_pk_add_f32 v[38:39], v[36:37], v[44:45]
	v_pk_add_f32 v[42:43], v[34:35], v[42:43]
	ds_read_b128 v[34:37], v17
	s_waitcnt lgkmcnt(1)
	v_pk_add_f32 v[44:45], v[38:39], v[32:33]
	ds_read_b128 v[38:41], v18
	v_pk_add_f32 v[42:43], v[42:43], v[30:31]
	ds_read_b128 v[30:33], v19
	s_waitcnt lgkmcnt(2)
	v_pk_add_f32 v[34:35], v[42:43], v[34:35]
	v_pk_add_f32 v[36:37], v[44:45], v[36:37]
	s_waitcnt lgkmcnt(1)
	v_pk_add_f32 v[34:35], v[34:35], v[38:39]
	v_pk_add_f32 v[36:37], v[36:37], v[40:41]
	s_waitcnt lgkmcnt(0)
	v_pk_add_f32 v[30:31], v[34:35], v[30:31]
	v_add_u32_e32 v34, s29, v20
	v_and_b32_e32 v0, 0x3f0, v34
	v_or_b32_e32 v35, v0, v11
	v_pk_add_f32 v[32:33], v[36:37], v[32:33]
	v_add_u32_e32 v36, 0xfffffe00, v35
	v_cmp_gt_u32_e32 vcc, s23, v0
	v_ashrrev_i32_e32 v34, 10, v34
	v_mov_b32_e32 v37, s13
	v_cndmask_b32_e32 v0, v36, v35, vcc
	v_mov_b32_e32 v36, s15
	v_ashrrev_i32_e32 v35, 31, v34
	v_cndmask_b32_e32 v37, v36, v37, vcc
	v_mov_b32_e32 v36, s14
	v_mov_b32_e32 v38, s12
	v_cndmask_b32_e32 v36, v36, v38, vcc
	v_lshlrev_b64 v[38:39], 20, v[34:35]
	v_lshl_add_u64 v[36:37], v[36:37], 0, v[38:39]
	v_lshlrev_b64 v[38:39], 11, v[8:9]
	v_lshl_add_u64 v[36:37], v[36:37], 0, v[38:39]
	v_pk_mul_f32 v[30:31], v[10:11], v[30:31] op_sel_hi:[0,1]
	v_pk_mul_f32 v[32:33], v[10:11], v[32:33] op_sel_hi:[0,1]
	v_lshl_add_u64 v[36:37], v[0:1], 2, v[36:37]
	v_mov_b32_e32 v10, s22
	v_mov_b32_e32 v35, s20
	global_store_dwordx4 v[36:37], v[30:33], off
	v_cndmask_b32_e32 v37, v10, v35, vcc
	v_mov_b32_e32 v10, s21
	v_mov_b32_e32 v35, s19
	v_cndmask_b32_e32 v36, v10, v35, vcc
	v_mul_hi_i32_i24_e32 v35, 0x280000, v34
	v_mul_i32_i24_e32 v34, 0x280000, v34
	v_lshl_add_u64 v[34:35], v[36:37], 0, v[34:35]
	v_lshlrev_b64 v[8:9], 10, v[8:9]
	v_lshl_add_u64 v[8:9], v[34:35], 0, v[8:9]
	v_lshl_add_u64 v[8:9], v[0:1], 1, v[8:9]
	v_cvt_pk_bf16_f32 v30, v30, v31
	v_cvt_pk_bf16_f32 v31, v32, v33
	global_store_dwordx2 v[8:9], v[30:31], off
	s_and_b64 exec, exec, s[6:7]
	s_cbranch_execz .LBB0_332
	ds_read_b128 v[30:33], v21 offset:16384
	ds_read_b128 v[34:37], v14 offset:8192
	ds_read_b128 v[38:41], v21 offset:32768
	ds_read_b128 v[42:45], v21 offset:49152
	v_add_u32_e32 v10, s29, v26
	v_and_b32_e32 v0, 0x3f0, v10
	s_waitcnt lgkmcnt(2)
	v_pk_add_f32 v[8:9], v[36:37], v[32:33]
	v_pk_add_f32 v[34:35], v[34:35], v[30:31]
	ds_read_b128 v[30:33], v22
	s_waitcnt lgkmcnt(2)
	v_pk_add_f32 v[34:35], v[34:35], v[38:39]
	v_pk_add_f32 v[8:9], v[8:9], v[40:41]
	s_waitcnt lgkmcnt(1)
	v_pk_add_f32 v[42:43], v[34:35], v[42:43]
	ds_read_b128 v[34:37], v23
	v_pk_add_f32 v[8:9], v[8:9], v[44:45]
	ds_read_b128 v[38:41], v24
	s_waitcnt lgkmcnt(2)
	v_pk_add_f32 v[8:9], v[8:9], v[32:33]
	v_pk_add_f32 v[42:43], v[42:43], v[30:31]
	ds_read_b128 v[30:33], v25
	s_waitcnt lgkmcnt(2)
	v_pk_add_f32 v[8:9], v[8:9], v[36:37]
	v_pk_add_f32 v[34:35], v[42:43], v[34:35]
	s_waitcnt lgkmcnt(1)
	v_pk_add_f32 v[8:9], v[8:9], v[40:41]
	v_cmp_gt_u32_e32 vcc, s23, v0
	s_waitcnt lgkmcnt(0)
	v_pk_add_f32 v[8:9], v[8:9], v[32:33]
	v_or_b32_e32 v32, v0, v11
	v_add_u32_e32 v33, 0xfffffe00, v32
	v_pk_add_f32 v[34:35], v[34:35], v[38:39]
	v_cndmask_b32_e32 v0, v33, v32, vcc
	v_ashrrev_i32_e32 v36, 10, v10
	v_mov_b32_e32 v10, s15
	v_mov_b32_e32 v32, s13
	v_pk_add_f32 v[30:31], v[34:35], v[30:31]
	v_add3_u32 v34, v13, v27, s28
	v_ashrrev_i32_e32 v37, 31, v36
	v_cndmask_b32_e32 v33, v10, v32, vcc
	v_mov_b32_e32 v10, s14
	v_mov_b32_e32 v32, s12
	v_ashrrev_i32_e32 v35, 31, v34
	v_cndmask_b32_e32 v32, v10, v32, vcc
	v_lshlrev_b64 v[38:39], 20, v[36:37]
	v_lshl_add_u64 v[32:33], v[32:33], 0, v[38:39]
	v_lshlrev_b64 v[38:39], 11, v[34:35]
	v_lshl_add_u64 v[38:39], v[32:33], 0, v[38:39]
	v_pk_mul_f32 v[30:31], v[6:7], v[30:31] op_sel_hi:[0,1]
	v_pk_mul_f32 v[32:33], v[6:7], v[8:9] op_sel_hi:[0,1]
	v_lshl_add_u64 v[8:9], v[0:1], 2, v[38:39]
	global_store_dwordx4 v[8:9], v[30:33], off
	v_mov_b32_e32 v6, s22
	v_mov_b32_e32 v8, s20
	v_cndmask_b32_e32 v9, v6, v8, vcc
	v_mov_b32_e32 v6, s21
	v_mov_b32_e32 v8, s19
	v_cndmask_b32_e32 v8, v6, v8, vcc
	v_mul_hi_i32_i24_e32 v37, 0x280000, v36
	v_mul_i32_i24_e32 v36, 0x280000, v36
	v_lshl_add_u64 v[8:9], v[8:9], 0, v[36:37]
	v_lshlrev_b64 v[34:35], 10, v[34:35]
	v_lshl_add_u64 v[8:9], v[8:9], 0, v[34:35]
	v_lshl_add_u64 v[8:9], v[0:1], 1, v[8:9]
	v_cvt_pk_bf16_f32 v30, v30, v31
	v_cvt_pk_bf16_f32 v31, v32, v33
	global_store_dwordx2 v[8:9], v[30:31], off
	s_branch .LBB0_332

.LBB0_1276:
	s_ashr_i32 s21, s20, 31
	s_lshr_b32 s21, s21, 30
	s_add_i32 s21, s20, s21
	s_ashr_i32 s21, s21, 2
	s_lshl_b32 s22, s21, 8
	s_sub_i32 s22, 0, s22
	v_add3_u32 v15, v17, v23, s22
	v_mov_b32_e32 v0, 1.0
	v_add_u32_e32 v12, 0x4000, v15
	s_and_saveexec_b64 s[36:37], s[0:1]
	s_cbranch_execz .LBB0_1278
	v_ashrrev_i32_e32 v13, 31, v12
	v_lshl_add_u64 v[120:121], v[12:13], 3, s[70:71]
	global_load_dwordx2 v[120:121], v[120:121], off
.LBB0_1278:
	s_or_b64 exec, exec, s[36:37]
	v_add_u32_e32 v2, s22, v23
	v_ashrrev_i32_e32 v3, 31, v2
	v_lshlrev_b64 v[2:3], 11, v[2:3]
	v_lshl_add_u64 v[80:81], v[6:7], 0, v[2:3]
	v_add_co_u32_e32 v84, vcc, 0x8000, v80
	s_lshl_b32 s21, s21, 5
	s_nop 0
	v_addc_co_u32_e32 v85, vcc, 0, v81, vcc
	v_or_b32_e32 v2, s21, v16
	v_add_co_u32_e32 v86, vcc, 0x10000, v80
	v_ashrrev_i32_e32 v3, 31, v2
	s_nop 0
	v_addc_co_u32_e32 v87, vcc, 0, v81, vcc
	v_lshlrev_b64 v[2:3], 11, v[2:3]
	v_add_co_u32_e32 v92, vcc, 0x18000, v80
	v_lshl_add_u64 v[82:83], v[8:9], 0, v[2:3]
	s_nop 0
	v_addc_co_u32_e32 v93, vcc, 0, v81, vcc
	v_add_co_u32_e32 v96, vcc, s50, v82
	global_load_dwordx4 v[2:5], v[80:81], off
	global_load_dwordx4 v[24:27], v[82:83], off
	v_addc_co_u32_e32 v97, vcc, 0, v83, vcc
	global_load_dwordx4 v[28:31], v[84:85], off
	global_load_dwordx4 v[32:35], v[86:87], off
	global_load_dwordx4 v[36:39], v[92:93], off
	global_load_dwordx4 v[40:43], v[80:81], off offset:64
	global_load_dwordx4 v[44:47], v[82:83], off offset:64
	global_load_dwordx4 v[48:51], v[84:85], off offset:64
	global_load_dwordx4 v[56:59], v[86:87], off offset:64
	global_load_dwordx4 v[68:71], v[96:97], off
	global_load_dwordx4 v[72:75], v[92:93], off offset:64
	global_load_dwordx4 v[76:79], v[96:97], off offset:64
	v_add_u32_e32 v13, s19, v18
	s_waitcnt vmcnt(0)
	s_and_saveexec_b64 s[36:37], s[0:1]
	v_ffbh_u32_e32 v122, v121
	v_min_u32_e32 v122, 32, v122
	v_lshlrev_b64 v[120:121], v122, v[120:121]
	v_min_u32_e32 v120, 1, v120
	v_or_b32_e32 v120, v121, v120
	v_cvt_f32_u32_e32 v120, v120
	v_sub_u32_e32 v121, 32, v122
	v_ldexp_f32 v120, v120, v121
	v_fmamk_f32 v120, v120, 0x30800000, v207
	v_mul_f32_e32 v121, 0x4b800000, v120
	v_cmp_gt_f32_e32 vcc, s16, v120
	s_nop 1
	v_cndmask_b32_e32 v120, v120, v121, vcc
	v_rsq_f32_e32 v120, v120
	s_nop 0
	v_mul_f32_e32 v121, 0x45800000, v120
	v_cndmask_b32_e32 v0, v120, v121, vcc
	s_or_b64 exec, exec, s[36:37]
	v_mfma_f32_16x16x32_bf16 v[52:55], v[24:27], v[2:5], 0
	v_mfma_f32_16x16x32_bf16 v[2:5], v[68:71], v[2:5], 0
	v_mfma_f32_16x16x32_bf16 v[60:63], v[24:27], v[28:31], 0
	v_mfma_f32_16x16x32_bf16 v[64:67], v[24:27], v[32:35], 0
	v_mfma_f32_16x16x32_bf16 v[24:27], v[24:27], v[36:39], 0
	v_mfma_f32_16x16x32_bf16 v[52:55], v[44:47], v[40:43], v[52:55]
	v_mfma_f32_16x16x32_bf16 v[2:5], v[76:79], v[40:43], v[2:5]
	global_load_dwordx4 v[40:43], v[82:83], off offset:128
	v_mfma_f32_16x16x32_bf16 v[28:31], v[68:71], v[28:31], 0
	v_mfma_f32_16x16x32_bf16 v[32:35], v[68:71], v[32:35], 0
	v_mfma_f32_16x16x32_bf16 v[36:39], v[68:71], v[36:39], 0
	v_mfma_f32_16x16x32_bf16 v[60:63], v[44:47], v[48:51], v[60:63]
	v_mfma_f32_16x16x32_bf16 v[64:67], v[44:47], v[56:59], v[64:67]
	v_mfma_f32_16x16x32_bf16 v[24:27], v[44:47], v[72:75], v[24:27]
	global_load_dwordx4 v[44:47], v[80:81], off offset:128
	v_mfma_f32_16x16x32_bf16 v[28:31], v[76:79], v[48:51], v[28:31]
	v_mfma_f32_16x16x32_bf16 v[32:35], v[76:79], v[56:59], v[32:35]
	global_load_dwordx4 v[48:51], v[84:85], off offset:128
	global_load_dwordx4 v[56:59], v[80:81], off offset:192
	global_load_dwordx4 v[68:71], v[82:83], off offset:192
	v_mfma_f32_16x16x32_bf16 v[36:39], v[76:79], v[72:75], v[36:39]
	global_load_dwordx4 v[72:75], v[86:87], off offset:128
	global_load_dwordx4 v[76:79], v[84:85], off offset:192
	global_load_dwordx4 v[80:83], v[92:93], off offset:128
	s_nop 0
	global_load_dwordx4 v[84:87], v[86:87], off offset:192
	s_nop 0
	global_load_dwordx4 v[88:91], v[96:97], off offset:128
	s_nop 0
	global_load_dwordx4 v[92:95], v[92:93], off offset:192
	s_waitcnt vmcnt(1)
	v_mfma_f32_16x16x32_bf16 v[28:31], v[88:91], v[48:51], v[28:31]
	v_mfma_f32_16x16x32_bf16 v[52:55], v[40:43], v[44:47], v[52:55]
	v_mfma_f32_16x16x32_bf16 v[60:63], v[40:43], v[48:51], v[60:63]
	v_mfma_f32_16x16x32_bf16 v[64:67], v[40:43], v[72:75], v[64:67]
	v_mfma_f32_16x16x32_bf16 v[24:27], v[40:43], v[80:83], v[24:27]
	global_load_dwordx4 v[40:43], v[96:97], off offset:192
	v_mfma_f32_16x16x32_bf16 v[2:5], v[88:91], v[44:47], v[2:5]
	v_mfma_f32_16x16x32_bf16 v[32:35], v[88:91], v[72:75], v[32:35]
	v_mfma_f32_16x16x32_bf16 v[44:47], v[68:71], v[56:59], v[52:55]
	s_waitcnt vmcnt(0)
	v_mfma_f32_16x16x32_bf16 v[2:5], v[40:43], v[56:59], v[2:5]
	s_nop 5
	ds_write_b128 v13, v[44:47]
	v_mfma_f32_16x16x32_bf16 v[48:51], v[68:71], v[76:79], v[60:63]
	v_mfma_f32_16x16x32_bf16 v[36:39], v[88:91], v[80:83], v[36:39]
	v_mfma_f32_16x16x32_bf16 v[28:31], v[40:43], v[76:79], v[28:31]
	ds_write_b128 v13, v[2:5] offset:1024
	s_nop 4
	ds_write_b128 v13, v[48:51] offset:2048
	s_nop 0
	ds_write_b128 v13, v[28:31] offset:3072
	v_mfma_f32_16x16x32_bf16 v[52:55], v[68:71], v[84:87], v[64:67]
	v_mfma_f32_16x16x32_bf16 v[32:35], v[40:43], v[84:87], v[32:35]
	v_mfma_f32_16x16x32_bf16 v[2:5], v[68:71], v[92:95], v[24:27]
	s_nop 5
	ds_write_b128 v13, v[52:55] offset:4096
	ds_write_b128 v13, v[32:35] offset:5120
	ds_write_b128 v13, v[2:5] offset:6144
	v_mfma_f32_16x16x32_bf16 v[2:5], v[40:43], v[92:95], v[36:39]
	s_nop 7
	ds_write_b128 v13, v[2:5] offset:7168
	s_waitcnt lgkmcnt(0)
	s_barrier
	s_and_saveexec_b64 s[36:37], s[0:1]
	s_cbranch_execz .LBB0_1275
	ds_read_b128 v[2:5], v19
	ds_read_b128 v[26:29], v20 offset:8192
	v_add_u32_e32 v24, s21, v21
	v_or_b32_e32 v14, v24, v22
	s_movk_i32 s12, 0x3ff
	v_cmp_lt_i32_e32 vcc, s12, v14
	s_waitcnt lgkmcnt(0)
	v_pk_add_f32 v[28:29], v[4:5], v[28:29]
	v_pk_add_f32 v[26:27], v[2:3], v[26:27]
	ds_read_b128 v[2:5], v20 offset:16384
	s_waitcnt lgkmcnt(0)
	v_pk_add_f32 v[28:29], v[28:29], v[4:5]
	v_pk_add_f32 v[26:27], v[26:27], v[2:3]
	ds_read_b128 v[2:5], v20 offset:24576
	s_waitcnt lgkmcnt(0)
	v_pk_add_f32 v[28:29], v[28:29], v[4:5]
	v_pk_add_f32 v[26:27], v[26:27], v[2:3]
	ds_read_b128 v[2:5], v20 offset:32768
	s_waitcnt lgkmcnt(0)
	v_pk_add_f32 v[28:29], v[28:29], v[4:5]
	v_pk_add_f32 v[26:27], v[26:27], v[2:3]
	ds_read_b128 v[2:5], v20 offset:40960
	s_waitcnt lgkmcnt(0)
	v_pk_add_f32 v[28:29], v[28:29], v[4:5]
	v_pk_add_f32 v[26:27], v[26:27], v[2:3]
	ds_read_b128 v[2:5], v20 offset:49152
	s_waitcnt lgkmcnt(0)
	v_pk_add_f32 v[28:29], v[28:29], v[4:5]
	v_pk_add_f32 v[26:27], v[26:27], v[2:3]
	ds_read_b128 v[2:5], v20 offset:57344
	s_waitcnt lgkmcnt(0)
	v_pk_add_f32 v[4:5], v[28:29], v[4:5]
	v_pk_add_f32 v[2:3], v[26:27], v[2:3]
	v_pk_mul_f32 v[4:5], v[0:1], v[4:5] op_sel_hi:[0,1]
	v_pk_mul_f32 v[2:3], v[0:1], v[2:3] op_sel_hi:[0,1]
	s_and_saveexec_b64 s[22:23], vcc
	s_xor_b64 s[40:41], exec, s[22:23]
	s_cbranch_execz .LBB0_1285
	s_movk_i32 s21, 0x3fff
	v_cmp_lt_i32_e64 s[42:43], s21, v12
	s_movk_i32 s21, 0x5ff
	v_cmp_lt_u32_e32 vcc, s21, v24
	v_mov_b32_e32 v0, 0x2152c00
	v_mov_b32_e32 v24, 0x2172c00
	s_movk_i32 s12, 0x4000
	v_cndmask_b32_e32 v0, v0, v24, vcc
	v_cndmask_b32_e32 v24, v211, v221, vcc
	v_cmp_gt_i32_e64 s[38:39], s12, v12
	v_cndmask_b32_e64 v12, v12, v15, s[42:43]
	v_cndmask_b32_e64 v0, v24, v0, s[42:43]
	v_ashrrev_i32_e32 v13, 31, v12
	v_lshlrev_b32_e32 v0, 2, v0
	v_and_b32_e32 v14, 0x1fc, v14
	v_lshl_add_u64 v[24:25], s[52:53], 0, v[0:1]
	v_lshlrev_b64 v[26:27], 11, v[12:13]
	v_lshl_add_u64 v[24:25], v[24:25], 0, v[26:27]
	v_lshlrev_b32_e32 v0, 2, v14
	v_lshl_add_u64 v[24:25], v[24:25], 0, v[0:1]
	global_store_dwordx4 v[24:25], v[2:5], off
	v_lshlrev_b32_e32 v0, 1, v14
	s_nop 0
	v_cvt_pk_bf16_f32 v2, v2, v3
	v_cvt_pk_bf16_f32 v3, v4, v5
	s_and_saveexec_b64 s[22:23], s[38:39]
	s_xor_b64 s[38:39], exec, s[22:23]
	s_cbranch_execz .LBB0_1282
	v_lshlrev_b64 v[4:5], 9, v[12:13]
	v_mov_b32_e32 v12, s79
	v_mov_b32_e32 v13, s4
	v_cndmask_b32_e32 v13, v12, v13, vcc
	v_mov_b32_e32 v12, s78
	v_mov_b32_e32 v14, s33
	v_cndmask_b32_e32 v12, v12, v14, vcc
	v_lshl_add_u64 v[4:5], v[4:5], 1, v[12:13]
	v_lshl_add_u64 v[4:5], v[4:5], 0, v[0:1]
	global_store_dwordx2 v[4:5], v[2:3], off
